# phase 3 chunk attention: gate rows of both row groups loaded at item start; the epilogue no longer waits for the item's own stores
# speedup vs baseline: 1.0113x; 1.0022x over previous
; DI void attn_block2(const Params& p, int bh, int cp, char* lds) {
;     ...
;     const int b = bh >> 3, h = bh & 7, c0 = 2 * cp, cq = c0 + (wave >> 1);
;     const int qposA = (wave & 1) * 32 + (lane & 15); const int qrowA = b * 8192 + cq * 64 + qposA;
;     float* tab = (float*)(lds + 49152);
;     __syncthreads();
;     for (int i = tid; i < 257; i += 256) tab[i] = p.relb[h * 257 + i] * LOG2E;
;     QG A, B;
;     { const u16* qp = proj + (size_t)qrowA * NC + C_Q + h * 64 + 8 * (lane >> 4); A.q0 = *(const bf16x8*)qp; A.q1 = *(const bf16x8*)(qp + 32);
;       const u16* qb = qp + (size_t)16 * NC; B.q0 = *(const bf16x8*)qb; B.q1 = *(const bf16x8*)(qb + 32); }
;     A.m = -INFINITY; A.l = 0.f; B.m = -INFINITY; B.l = 0.f;
; #pragma unroll
;     for (int dt = 0; dt < 4; ++dt) { A.o[dt] = (f32x4){0.f, 0.f, 0.f, 0.f}; B.o[dt] = (f32x4){0.f, 0.f, 0.f, 0.f}; }
;     unsigned soff[2];
; #pragma unroll
;     for (int i = 0; i < 2; ++i) { const int row = 8 * (i * 4 + wave) + (lane >> 3); const int ch = (lane & 7) ^ ((row >> 1) & 7); soff[i] = (unsigned)(row * NC + ch * 8); }
;     const u16* kbase = proj + (size_t)(b * 8192) * NC + h * 64;
;     ...
;     const int lo = c0 >= 8 ? c0 - 8 : 0, hi = c0 + 1;
;     __syncthreads();
;     ASTAGE2(0, lo); ASTAGE2(1, lo + 1);
;     int buf = 0;
;     for (int kc = lo; kc <= hi; ++kc) {
;         if (kc < hi) asm volatile("s_waitcnt vmcnt(4) lgkmcnt(0)" ::: "memory"); else asm volatile("s_waitcnt vmcnt(0) lgkmcnt(0)" ::: "memory");
;         __builtin_amdgcn_s_barrier();
;         asm volatile("" ::: "memory");
;         const int nb2 = buf >= 1 ? buf - 1 : 2;
;         if (kc + 2 <= hi) ASTAGE2(nb2, kc + 2);
.LBB0_396:
	s_or_b64 exec, exec, s[6:7]
	s_sub_i32 s3, s33, 32
	s_and_b32 s2, s3, -2
	s_ashr_i32 s30, s4, 6
	s_sub_i32 s36, 0x7e, s2
	s_ashr_i32 s6, s4, 7
	s_add_i32 s4, s6, s36
	s_lshl_b32 s7, s30, 5
	s_and_b32 s7, s7, 32
	v_and_b32_e32 v2, 15, v82
	s_lshl_b32 s4, s4, 6
	v_or_b32_e32 v3, s7, v2
	s_add_i32 s4, s4, s83
	v_or_b32_e32 v83, s4, v3
	v_mov_b64_e32 v[4:5], s[68:69]
	v_mad_i64_i32 v[4:5], s[28:29], v83, s43, v[4:5]
	s_lshl_b32 s4, s88, 7
	v_lshl_add_u64 v[4:5], v[4:5], 0, s[4:5]
	v_and_b32_e32 v158, 48, v82
	v_lshl_add_u64 v[4:5], v[4:5], 0, v[158:159]
	s_mov_b32 s28, 0x21000
	global_load_dwordx4 v[18:21], v[4:5], off
	global_load_dwordx4 v[22:25], v[4:5], off offset:64
	v_add_co_u32_e32 v4, vcc, s28, v4
	v_bfe_u32 v3, v82, 3, 3
	s_nop 0
	v_addc_co_u32_e32 v5, vcc, 0, v5, vcc
	v_lshl_or_b32 v3, s30, 3, v3
	s_movk_i32 s28, 0x1080
	s_add_u32 s4, s86, s4
	global_load_dwordx4 v[26:29], v[4:5], off
	global_load_dwordx4 v[30:33], v[4:5], off offset:64
	v_mad_i64_i32 v[246:247], vcc, v83, s43, 0
	s_mul_i32 s100, s88, 0x80
	v_and_b32_e32 v248, 63, v82
	s_mov_b32 s101, 0
	v_lshl_add_u64 v[246:247], s[54:55], 0, v[246:247]
	v_lshrrev_b32_e32 v248, 1, v248
	v_mov_b32_e32 v249, 0
	v_and_b32_e32 v248, 24, v248
	v_lshl_add_u64 v[246:247], v[246:247], 0, s[100:101]
	v_lshl_add_u64 v[246:247], v[246:247], 0, v[248:249]
	v_lshl_add_u64 v[246:247], v[246:247], 0, s[12:13]
	global_load_dwordx2 v[238:239], v[246:247], off offset:32
	global_load_dwordx2 v[240:241], v[246:247], off offset:64
	global_load_dwordx2 v[242:243], v[246:247], off offset:96
	global_load_dwordx2 v[244:245], v[246:247], off
	v_or_b32_e32 v250, 16, v83
	v_mad_i64_i32 v[246:247], vcc, v250, s43, 0
	v_lshl_add_u64 v[246:247], s[54:55], 0, v[246:247]
	v_lshl_add_u64 v[246:247], v[246:247], 0, s[100:101]
	v_lshl_add_u64 v[246:247], v[246:247], 0, v[248:249]
	v_lshl_add_u64 v[246:247], v[246:247], 0, s[12:13]
	global_load_dwordx2 v[250:251], v[246:247], off
	global_load_dwordx2 v[252:253], v[246:247], off offset:32
	global_load_dwordx2 v[254:255], v[246:247], off offset:64
	global_load_dwordx2 v[248:249], v[246:247], off offset:96
	v_lshrrev_b32_e32 v4, 1, v3
	v_mul_lo_u32 v3, v3, s28
	s_addc_u32 s37, s87, 0
	s_sub_i32 s28, 0x76, s2
	s_cmpk_lt_u32 s3, 0x78
	s_cselect_b32 s89, s28, 0
	s_mul_i32 s28, s89, 0x42000
	v_xor_b32_e32 v4, v4, v82
	s_ashr_i32 s29, s28, 31
	v_lshlrev_b32_e32 v4, 3, v4
	s_lshl_b64 s[28:29], s[28:29], 1
	v_and_or_b32 v158, v4, 56, v3
	s_add_u32 s28, s4, s28
	s_addc_u32 s29, s37, s29
	s_lshl_b32 s30, s30, 10
	v_lshlrev_b64 v[4:5], 1, v[158:159]
	v_lshl_add_u64 v[6:7], s[28:29], 0, v[4:5]
	s_add_i32 s90, s30, 0
	v_lshl_add_u64 v[8:9], v[6:7], 0, s[0:1]
	s_mov_b32 m0, s90
	v_add_u32_e32 v84, 0x21000, v158
	s_waitcnt lgkmcnt(0)
	s_barrier
	global_load_lds_dwordx4 v[8:9], off
	v_lshl_add_u64 v[6:7], v[6:7], 0, s[8:9]
	s_add_i32 m0, s90, 0x6000
	v_mov_b32_e32 v85, v159
	global_load_lds_dwordx4 v[6:7], off
	v_lshlrev_b64 v[6:7], 1, v[84:85]
	v_lshl_add_u64 v[8:9], s[28:29], 0, v[6:7]
	v_lshl_add_u64 v[10:11], v[8:9], 0, s[0:1]
	s_add_i32 m0, s90, 0x1000
	v_lshl_add_u64 v[8:9], v[8:9], 0, s[8:9]
	global_load_lds_dwordx4 v[10:11], off
	s_add_i32 m0, s90, 0x7000
	s_add_u32 s28, s28, 0x84000
	s_addc_u32 s29, s29, 0
	v_lshl_add_u64 v[4:5], s[28:29], 0, v[4:5]
	global_load_lds_dwordx4 v[8:9], off
	v_lshl_add_u64 v[8:9], v[4:5], 0, s[0:1]
	s_add_i32 m0, s90, 0x2000
	v_lshl_add_u64 v[4:5], v[4:5], 0, s[8:9]
	global_load_lds_dwordx4 v[8:9], off
	s_add_i32 m0, s90, 0x8000
	s_sub_i32 s91, 0x7f, s2
	global_load_lds_dwordx4 v[4:5], off
	v_lshl_add_u64 v[4:5], s[28:29], 0, v[6:7]
	v_lshl_add_u64 v[6:7], v[4:5], 0, s[0:1]
	s_add_i32 m0, s90, 0x3000
	v_lshl_add_u64 v[4:5], v[4:5], 0, s[8:9]
	global_load_lds_dwordx4 v[6:7], off
	s_add_i32 m0, s90, 0x9000
	v_and_b32_e32 v106, 63, v82
	global_load_lds_dwordx4 v[4:5], off
	s_cmp_le_i32 s89, s91
	s_mov_b32 s92, 0
	s_cbranch_scc0 .LBB0_416
	ds_read_b32 v207, v159 offset:50176
	v_lshrrev_b32_e32 v4, 4, v106
	v_bfe_u32 v5, v82, 1, 3
	v_lshrrev_b32_e32 v3, 1, v82
	v_bitop3_b32 v5, v4, v5, 4 bitop3:0x36
	s_lshl_b32 s28, s6, 6
	v_bitop3_b32 v6, v3, v4, 7 bitop3:0x6c
	v_lshlrev_b32_e32 v108, 4, v5
	v_lshlrev_b32_e32 v4, 2, v4
	v_lshrrev_b32_e32 v5, 2, v2
	s_or_b32 s7, s28, s7
	v_lshlrev_b32_e32 v107, 4, v6
	v_lshlrev_b32_e32 v6, 3, v106
	v_or_b32_e32 v5, v4, v5
	s_addk_i32 s7, 0x1f90
	v_and_b32_e32 v6, 8, v6
	v_lshlrev_b32_e32 v110, 7, v5
	v_lshrrev_b32_e32 v5, 1, v5
	v_lshl_add_u32 v115, v2, 7, 0
	v_add_u32_e32 v2, s7, v2
	v_add_u32_e32 v109, 0, v6
	v_bfe_u32 v6, v82, 1, 1
	v_bitop3_b32 v3, v5, v3, 1 bitop3:0x78
	v_sub_u32_e32 v2, v2, v4
	s_lshl_b32 s7, s89, 6
	s_lshl_b32 s3, s3, 6
	v_lshlrev_b32_e32 v111, 4, v3
	v_bitop3_b32 v3, v5, v6, 2 bitop3:0x1e
	v_subrev_u32_e32 v2, s7, v2
	s_and_b32 s3, s3, 0xffffff80
	v_lshlrev_b32_e32 v112, 4, v3
	v_bitop3_b32 v3, v5, v6, 4 bitop3:0x1e
	v_subrev_u32_e32 v116, s3, v2
	s_sub_i32 s3, s6, s89
	v_lshlrev_b32_e32 v113, 4, v3
	v_bitop3_b32 v3, v5, v6, 6 bitop3:0x1e
	s_sub_i32 s2, s3, s2
	v_mov_b32_e32 v14, 0
	v_lshlrev_b32_e32 v114, 4, v3
	s_add_i32 s93, s2, 0x7e
	s_add_i32 s94, s7, 0x80
	v_mov_b32_e32 v118, 0xff800000
	v_mov_b32_e32 v117, 0xff800000
	v_mov_b32_e32 v15, v14
	v_mov_b32_e32 v16, v14
	v_mov_b32_e32 v17, v14
	v_mov_b32_e32 v10, v14
	v_mov_b32_e32 v11, v14
	v_mov_b32_e32 v12, v14
	v_mov_b32_e32 v13, v14
	v_mov_b32_e32 v6, v14
	v_mov_b32_e32 v7, v14
	v_mov_b32_e32 v8, v14
	v_mov_b32_e32 v9, v14
	v_mov_b32_e32 v2, v14
	v_mov_b32_e32 v3, v14
	v_mov_b32_e32 v4, v14
	v_mov_b32_e32 v5, v14
	v_mov_b32_e32 v46, v14
	v_mov_b32_e32 v47, v14
	v_mov_b32_e32 v48, v14
	v_mov_b32_e32 v49, v14
	v_mov_b32_e32 v38, v14
	v_mov_b32_e32 v39, v14
	v_mov_b32_e32 v40, v14
	v_mov_b32_e32 v41, v14
	v_mov_b32_e32 v42, v14
	v_mov_b32_e32 v43, v14
	v_mov_b32_e32 v44, v14
	v_mov_b32_e32 v45, v14
	v_mov_b32_e32 v34, v14
	v_mov_b32_e32 v35, v14
	v_mov_b32_e32 v36, v14
	v_mov_b32_e32 v37, v14
	v_mov_b32_e32 v86, v14
	v_mov_b32_e32 v87, v14
	s_branch .LBB0_400

; DI unsigned pack2(float lo, float hi) { f32x2_t v = {lo, hi}; bf16x2_t b = __builtin_convertvector(v, bf16x2_t); return __builtin_bit_cast(unsigned, b); }
; DI float bflo(unsigned u) { return __uint_as_float(u << 16); }
; DI float bfhi(unsigned u) { return __uint_as_float(u & 0xffff0000u); }
; DI float rcpf_(float x) { return __builtin_amdgcn_rcpf(x); }
; DI float silu(float x) { return x * rcpf_(1.f + __expf(-x)); }
; DI float xadd16(float v) { const unsigned x = __float_as_uint(v); auto r = __builtin_amdgcn_permlane16_swap(x, x, false, false); return __uint_as_float(r[0]) + __uint_as_float(r[1]); }
; DI float xadd32(float v) { const unsigned x = __float_as_uint(v); auto r = __builtin_amdgcn_permlane32_swap(x, x, false, false); return __uint_as_float(r[0]) + __uint_as_float(r[1]); }
; DI void attn_finish(const Params& p, float l, const f32x4 (&o)[4], int qrow, int h, int lane) {
;     const int g = lane >> 4; const u16* proj = (const u16*)(p.ws + W_PROJ);
;     l = xadd16(l); l = xadd32(l);
;     const float inv = rcpf_(l);
;     u16* z = (u16*)(p.ws + W_XB) + (size_t)qrow * DM + h * 64; const u16* ga = proj + (size_t)qrow * NC + C_GA + h * 64;
;     uint2 w[4];
; #pragma unroll
;     for (int dt = 0; dt < 4; ++dt) { const int d = 16 * dt + 4 * g; const uint2 gg = *(const uint2*)(ga + d);
;         w[dt].x = pack2(o[dt][0] * inv * silu(bflo(gg.x)), o[dt][1] * inv * silu(bfhi(gg.x))); w[dt].y = pack2(o[dt][2] * inv * silu(bflo(gg.y)), o[dt][3] * inv * silu(bfhi(gg.y))); }
; #pragma unroll
;     for (int dt = 0; dt < 4; dt += 2) *(uint4*)(z + 16 * (dt + (g & 1)) + 8 * (g >> 1)) = widen16(w[dt], w[dt + 1]);
; DI void attn_block2(const Params& p, int bh, int cp, char* lds) {
;     ...
;     attn_finish(p, A.l, A.o, qrowA, h, lane);
.LBB0_417:
	s_waitcnt vmcnt(0)
	v_mad_i64_i32 v[18:19], s[2:3], v83, s43, 0
	s_lshl_b32 s2, s88, 6
	v_mov_b32_e32 v28, v67
	v_lshl_add_u64 v[18:19], s[54:55], 0, v[18:19]
	s_lshl_b32 s4, s2, 1
	v_lshrrev_b32_e32 v62, 1, v106
	v_permlane16_swap_b32_e32 v67, v28
	v_lshl_add_u64 v[20:21], v[18:19], 0, s[4:5]
	v_and_b32_e32 v158, 24, v62
	v_add_f32_e32 v28, v67, v28
	v_lshl_add_u64 v[20:21], v[20:21], 0, v[158:159]
	v_mov_b32_e32 v29, v28
	v_lshl_add_u64 v[22:23], v[20:21], 0, s[12:13]
	v_add_co_u32_e32 v20, vcc, 0x2bf5000, v20
	v_permlane32_swap_b32_e32 v28, v29
	s_nop 0
	v_addc_co_u32_e32 v21, vcc, 0, v21, vcc
	v_add_f32_e32 v28, v28, v29
	v_mov_b32_e32 v24, v238
	v_mov_b32_e32 v25, v239
	v_mov_b32_e32 v26, v240
	v_mov_b32_e32 v27, v241
	v_rcp_f32_e32 v30, v28
	v_mov_b32_e32 v28, v242
	v_mov_b32_e32 v29, v243
	v_mad_i64_i32 v[18:19], s[2:3], v83, s70, v[18:19]
	v_mov_b32_e32 v20, v244
	v_mov_b32_e32 v21, v245
	v_pk_mul_f32 v[22:23], v[34:35], v[30:31] op_sel_hi:[1,0]
	v_pk_mul_f32 v[32:33], v[36:37], v[30:31] op_sel_hi:[1,0]
	v_pk_mul_f32 v[34:35], v[42:43], v[30:31] op_sel_hi:[1,0]
	v_pk_mul_f32 v[36:37], v[44:45], v[30:31] op_sel_hi:[1,0]
	v_pk_mul_f32 v[38:39], v[38:39], v[30:31] op_sel_hi:[1,0]
	s_waitcnt vmcnt(0)
	v_and_b32_e32 v43, 0xffff0000, v24
	v_lshlrev_b32_e32 v44, 16, v26
	v_and_b32_e32 v45, 0xffff0000, v26
	v_lshlrev_b32_e32 v50, 16, v27
	v_and_b32_e32 v51, 0xffff0000, v27
	v_lshlrev_b32_e32 v42, 16, v24
	v_lshlrev_b32_e32 v26, 16, v20
	v_and_b32_e32 v27, 0xffff0000, v20
	v_lshlrev_b32_e32 v20, 16, v21
	v_and_b32_e32 v21, 0xffff0000, v21
	v_lshlrev_b32_e32 v24, 16, v25
	v_mul_f32_e32 v52, 0xbfb8aa3b, v43
	v_mul_f32_e32 v57, 0xbfb8aa3b, v50
	v_mul_f32_e32 v58, 0xbfb8aa3b, v51
	v_mul_f32_e32 v59, 0xbfb8aa3b, v26
	v_mul_f32_e32 v60, 0xbfb8aa3b, v27
	v_mul_f32_e32 v61, 0xbfb8aa3b, v20
	v_mul_f32_e32 v63, 0xbfb8aa3b, v21
	v_mul_f32_e32 v53, 0xbfb8aa3b, v24
	v_exp_f32_e32 v52, v52
	v_exp_f32_e32 v64, v57
	v_exp_f32_e32 v65, v58
	v_exp_f32_e32 v57, v59
	v_exp_f32_e32 v58, v60
	v_exp_f32_e32 v59, v61
	v_exp_f32_e32 v60, v63
	v_exp_f32_e32 v53, v53
	v_add_f32_e32 v61, 1.0, v52
	v_add_f32_e32 v70, 1.0, v57
	v_add_f32_e32 v71, 1.0, v58
	v_add_f32_e32 v72, 1.0, v59
	v_add_f32_e32 v73, 1.0, v60
	v_add_f32_e32 v63, 1.0, v53
	v_rcp_f32_e32 v53, v61
	v_rcp_f32_e32 v58, v70
	v_rcp_f32_e32 v59, v71
	v_rcp_f32_e32 v60, v72
	v_rcp_f32_e32 v61, v73
	v_mul_f32_e32 v55, 0xbfb8aa3b, v44
	v_mul_f32_e32 v56, 0xbfb8aa3b, v45
	v_exp_f32_e32 v55, v55
	v_exp_f32_e32 v56, v56
	v_pk_mul_f32 v[26:27], v[58:59], v[26:27]
	v_pk_mul_f32 v[20:21], v[60:61], v[20:21]
	v_mul_f32_e32 v31, 0xbfb8aa3b, v42
	v_pk_mul_f32 v[22:23], v[22:23], v[26:27]
	v_pk_mul_f32 v[20:21], v[32:33], v[20:21]
	v_exp_f32_e32 v31, v31
	v_add_f32_e32 v68, 1.0, v55
	v_add_f32_e32 v69, 1.0, v56
	v_cvt_pk_bf16_f32 v22, v22, v23
	v_cvt_pk_bf16_f32 v23, v20, v21
	v_add_f32_e32 v20, 1.0, v64
	v_add_f32_e32 v21, 1.0, v65
	v_rcp_f32_e32 v56, v68
	v_rcp_f32_e32 v57, v69
	v_rcp_f32_e32 v20, v20
	v_rcp_f32_e32 v21, v21
	v_and_b32_e32 v25, 0xffff0000, v25
	v_mul_f32_e32 v54, 0xbfb8aa3b, v25
	v_exp_f32_e32 v54, v54
	v_add_f32_e32 v31, 1.0, v31
	v_pk_mul_f32 v[44:45], v[56:57], v[44:45]
	v_pk_mul_f32 v[32:33], v[40:41], v[30:31] op_sel_hi:[1,0]
	v_pk_mul_f32 v[20:21], v[20:21], v[50:51]
	v_pk_mul_f32 v[26:27], v[38:39], v[44:45]
	v_pk_mul_f32 v[20:21], v[32:33], v[20:21]
	v_cvt_pk_bf16_f32 v26, v26, v27
	v_cvt_pk_bf16_f32 v27, v20, v21
	v_lshlrev_b32_e32 v20, 16, v28
	v_add_f32_e32 v67, 1.0, v54
	v_mul_f32_e32 v21, 0xbfb8aa3b, v20
	v_rcp_f32_e32 v52, v31
	v_rcp_f32_e32 v54, v63
	v_rcp_f32_e32 v55, v67
	v_exp_f32_e32 v31, v21
	v_and_b32_e32 v21, 0xffff0000, v28
	v_mul_f32_e32 v28, 0xbfb8aa3b, v21
	v_exp_f32_e32 v28, v28
	v_pk_mul_f32 v[24:25], v[54:55], v[24:25]
	v_add_f32_e32 v31, 1.0, v31
	v_pk_mul_f32 v[36:37], v[36:37], v[24:25]
	v_add_f32_e32 v28, 1.0, v28
	v_cvt_pk_bf16_f32 v25, v36, v37
	v_lshlrev_b32_e32 v36, 16, v29
	v_rcp_f32_e32 v33, v28
	v_and_b32_e32 v37, 0xffff0000, v29
	v_mul_f32_e32 v28, 0xbfb8aa3b, v36
	v_exp_f32_e32 v28, v28
	v_mul_f32_e32 v29, 0xbfb8aa3b, v37
	v_rcp_f32_e32 v32, v31
	v_exp_f32_e32 v29, v29
	v_add_f32_e32 v28, 1.0, v28
	v_pk_mul_f32 v[42:43], v[52:53], v[42:43]
	v_pk_mul_f32 v[20:21], v[32:33], v[20:21]
	v_rcp_f32_e32 v32, v28
	v_add_f32_e32 v28, 1.0, v29
	v_rcp_f32_e32 v33, v28
	v_pk_mul_f32 v[34:35], v[34:35], v[42:43]
	v_permlane16_swap_b32_e32 v23, v25
	v_cvt_pk_bf16_f32 v24, v34, v35
	v_pk_mul_f32 v[34:35], v[46:47], v[30:31] op_sel_hi:[1,0]
	s_nop 0
	v_permlane16_swap_b32_e32 v22, v24
	v_pk_mul_f32 v[20:21], v[34:35], v[20:21]
	s_nop 0
	v_cvt_pk_bf16_f32 v28, v20, v21
	v_pk_mul_f32 v[20:21], v[48:49], v[30:31] op_sel_hi:[1,0]
	v_pk_mul_f32 v[30:31], v[32:33], v[36:37]
	v_or_b32_e32 v33, 16, v83
	v_pk_mul_f32 v[20:21], v[20:21], v[30:31]
	v_permlane16_swap_b32_e32 v26, v28
	v_cvt_pk_bf16_f32 v29, v20, v21
	v_lshl_add_u64 v[20:21], v[18:19], 0, s[4:5]
	v_and_b32_e32 v18, 16, v62
	v_mov_b32_e32 v19, v159
	v_lshl_add_u64 v[30:31], v[20:21], 0, v[18:19]
	v_and_b32_e32 v20, 16, v82
	v_lshlrev_b32_e32 v20, 1, v20
; DI unsigned pack2(float lo, float hi) { f32x2_t v = {lo, hi}; bf16x2_t b = __builtin_convertvector(v, bf16x2_t); return __builtin_bit_cast(unsigned, b); }
; DI float bflo(unsigned u) { return __uint_as_float(u << 16); }
; DI float bfhi(unsigned u) { return __uint_as_float(u & 0xffff0000u); }
; DI float rcpf_(float x) { return __builtin_amdgcn_rcpf(x); }
; DI float silu(float x) { return x * rcpf_(1.f + __expf(-x)); }
; DI float xadd16(float v) { const unsigned x = __float_as_uint(v); auto r = __builtin_amdgcn_permlane16_swap(x, x, false, false); return __uint_as_float(r[0]) + __uint_as_float(r[1]); }
; DI float xadd32(float v) { const unsigned x = __float_as_uint(v); auto r = __builtin_amdgcn_permlane32_swap(x, x, false, false); return __uint_as_float(r[0]) + __uint_as_float(r[1]); }
; DI void attn_finish(const Params& p, float l, const f32x4 (&o)[4], int qrow, int h, int lane) {
;     const int g = lane >> 4; const u16* proj = (const u16*)(p.ws + W_PROJ);
;     l = xadd16(l); l = xadd32(l);
;     const float inv = rcpf_(l);
;     u16* z = (u16*)(p.ws + W_XB) + (size_t)qrow * DM + h * 64; const u16* ga = proj + (size_t)qrow * NC + C_GA + h * 64;
;     uint2 w[4];
; #pragma unroll
;     for (int dt = 0; dt < 4; ++dt) { const int d = 16 * dt + 4 * g; const uint2 gg = *(const uint2*)(ga + d);
;         w[dt].x = pack2(o[dt][0] * inv * silu(bflo(gg.x)), o[dt][1] * inv * silu(bfhi(gg.x))); w[dt].y = pack2(o[dt][2] * inv * silu(bflo(gg.y)), o[dt][3] * inv * silu(bfhi(gg.y))); }
; #pragma unroll
;     for (int dt = 0; dt < 4; dt += 2) *(uint4*)(z + 16 * (dt + (g & 1)) + 8 * (g >> 1)) = widen16(w[dt], w[dt + 1]);
; DI void attn_block2(const Params& p, int bh, int cp, char* lds) {
;     ...
;     attn_finish(p, B.l, B.o, qrowA + 16, h, lane);
	v_mov_b32_e32 v21, v159
	v_lshl_add_u64 v[30:31], v[30:31], 0, v[20:21]
	global_store_dwordx4 v[30:31], v[22:25], off
	v_permlane16_swap_b32_e32 v27, v29
	s_nop 0
	v_mov_b64_e32 v[22:23], s[54:55]
	v_mad_i64_i32 v[22:23], s[2:3], v33, s43, v[22:23]
	v_lshl_add_u64 v[24:25], v[22:23], 0, s[4:5]
	v_lshl_add_u64 v[24:25], v[24:25], 0, v[158:159]
	s_mov_b32 s2, 0x2bf5000
	global_store_dwordx4 v[30:31], v[26:29], off offset:64
	v_mov_b32_e32 v32, v66
	s_nop 1
	v_permlane16_swap_b32_e32 v66, v32
	v_add_co_u32_e32 v26, vcc, s2, v24
	v_add_f32_e32 v32, v66, v32
	s_nop 0
	v_addc_co_u32_e32 v27, vcc, 0, v25, vcc
	v_mov_b32_e32 v26, v250
	v_mov_b32_e32 v27, v251
	v_lshl_add_u64 v[24:25], v[24:25], 0, s[12:13]
	v_mov_b32_e32 v28, v252
	v_mov_b32_e32 v29, v253
	v_mov_b32_e32 v30, v254
	v_mov_b32_e32 v31, v255
	v_mov_b32_e32 v34, v32
	v_mov_b32_e32 v24, v248
	v_mov_b32_e32 v25, v249
	s_nop 0
	v_permlane32_swap_b32_e32 v32, v34
	v_add_f32_e32 v32, v32, v34
	v_rcp_f32_e32 v32, v32
	v_lshlrev_b32_e32 v34, 16, v26
	v_mul_f32_e32 v35, 0xbfb8aa3b, v34
	v_exp_f32_e32 v36, v35
	v_and_b32_e32 v35, 0xffff0000, v26
	v_mul_f32_e32 v26, 0xbfb8aa3b, v35
	v_exp_f32_e32 v26, v26
	v_add_f32_e32 v36, 1.0, v36
	v_rcp_f32_e32 v36, v36
	v_pk_mul_f32 v[2:3], v[2:3], v[32:33] op_sel_hi:[1,0]
	v_add_f32_e32 v26, 1.0, v26
	v_rcp_f32_e32 v37, v26
	v_lshlrev_b32_e32 v26, 16, v27
	v_and_b32_e32 v27, 0xffff0000, v27
	v_mul_f32_e32 v38, 0xbfb8aa3b, v26
	v_mul_f32_e32 v39, 0xbfb8aa3b, v27
	v_exp_f32_e32 v38, v38
	v_exp_f32_e32 v39, v39
	v_pk_mul_f32 v[34:35], v[36:37], v[34:35]
	v_pk_mul_f32 v[4:5], v[4:5], v[32:33] op_sel_hi:[1,0]
	v_add_f32_e32 v36, 1.0, v38
	v_add_f32_e32 v37, 1.0, v39
	v_rcp_f32_e32 v36, v36
	v_rcp_f32_e32 v37, v37
	v_pk_mul_f32 v[2:3], v[2:3], v[34:35]
	v_pk_mul_f32 v[6:7], v[6:7], v[32:33] op_sel_hi:[1,0]
	v_cvt_pk_bf16_f32 v2, v2, v3
	v_pk_mul_f32 v[26:27], v[36:37], v[26:27]
	v_pk_mul_f32 v[10:11], v[10:11], v[32:33] op_sel_hi:[1,0]
	v_pk_mul_f32 v[4:5], v[4:5], v[26:27]
	s_nop 0
	v_cvt_pk_bf16_f32 v3, v4, v5
	v_lshlrev_b32_e32 v4, 16, v28
	v_mul_f32_e32 v5, 0xbfb8aa3b, v4
	v_exp_f32_e32 v26, v5
	v_and_b32_e32 v5, 0xffff0000, v28
	v_mul_f32_e32 v27, 0xbfb8aa3b, v5
	v_exp_f32_e32 v27, v27
	v_lshlrev_b32_e32 v28, 16, v29
	v_and_b32_e32 v29, 0xffff0000, v29
	v_add_f32_e32 v26, 1.0, v26
	v_add_f32_e32 v27, 1.0, v27
	v_mul_f32_e32 v34, 0xbfb8aa3b, v28
	v_mul_f32_e32 v35, 0xbfb8aa3b, v29
	v_rcp_f32_e32 v26, v26
	v_rcp_f32_e32 v27, v27
	v_exp_f32_e32 v34, v34
	v_exp_f32_e32 v35, v35
	v_pk_mul_f32 v[4:5], v[26:27], v[4:5]
	v_add_f32_e32 v26, 1.0, v34
	v_add_f32_e32 v27, 1.0, v35
	v_rcp_f32_e32 v26, v26
	v_rcp_f32_e32 v27, v27
	v_pk_mul_f32 v[4:5], v[6:7], v[4:5]
	v_pk_mul_f32 v[6:7], v[8:9], v[32:33] op_sel_hi:[1,0]
	v_cvt_pk_bf16_f32 v4, v4, v5
	v_pk_mul_f32 v[8:9], v[26:27], v[28:29]
	v_lshlrev_b32_e32 v26, 16, v31
	v_pk_mul_f32 v[6:7], v[6:7], v[8:9]
	v_and_b32_e32 v27, 0xffff0000, v31
	v_cvt_pk_bf16_f32 v5, v6, v7
	v_lshlrev_b32_e32 v6, 16, v30
	v_mul_f32_e32 v7, 0xbfb8aa3b, v6
	v_exp_f32_e32 v8, v7
	v_and_b32_e32 v7, 0xffff0000, v30
	v_mul_f32_e32 v9, 0xbfb8aa3b, v7
	v_exp_f32_e32 v9, v9
	v_add_f32_e32 v8, 1.0, v8
	v_mul_f32_e32 v28, 0xbfb8aa3b, v26
	v_mul_f32_e32 v29, 0xbfb8aa3b, v27
	v_add_f32_e32 v9, 1.0, v9
	v_rcp_f32_e32 v8, v8
	v_rcp_f32_e32 v9, v9
	v_exp_f32_e32 v28, v28
	v_exp_f32_e32 v29, v29
	v_permlane16_swap_b32_e32 v2, v4
	v_pk_mul_f32 v[6:7], v[8:9], v[6:7]
	v_add_f32_e32 v8, 1.0, v28
	v_add_f32_e32 v9, 1.0, v29
	v_rcp_f32_e32 v8, v8
	v_rcp_f32_e32 v9, v9
	v_pk_mul_f32 v[6:7], v[10:11], v[6:7]
	v_pk_mul_f32 v[10:11], v[12:13], v[32:33] op_sel_hi:[1,0]
	v_cvt_pk_bf16_f32 v6, v6, v7
	v_pk_mul_f32 v[8:9], v[8:9], v[26:27]
	v_pk_mul_f32 v[12:13], v[14:15], v[32:33] op_sel_hi:[1,0]
	v_pk_mul_f32 v[8:9], v[10:11], v[8:9]
	v_lshlrev_b32_e32 v14, 16, v25
	v_cvt_pk_bf16_f32 v7, v8, v9
	v_lshlrev_b32_e32 v8, 16, v24
	v_mul_f32_e32 v9, 0xbfb8aa3b, v8
	v_exp_f32_e32 v10, v9
	v_and_b32_e32 v9, 0xffff0000, v24
	v_mul_f32_e32 v11, 0xbfb8aa3b, v9
	v_exp_f32_e32 v11, v11
	v_and_b32_e32 v15, 0xffff0000, v25
	v_add_f32_e32 v10, 1.0, v10
	v_mul_f32_e32 v24, 0xbfb8aa3b, v14
	v_add_f32_e32 v11, 1.0, v11
	v_mul_f32_e32 v25, 0xbfb8aa3b, v15
	v_rcp_f32_e32 v10, v10
	v_rcp_f32_e32 v11, v11
	v_exp_f32_e32 v24, v24
	v_exp_f32_e32 v25, v25
	v_permlane16_swap_b32_e32 v3, v5
	v_pk_mul_f32 v[8:9], v[10:11], v[8:9]
	v_add_f32_e32 v10, 1.0, v24
	v_add_f32_e32 v11, 1.0, v25
	v_rcp_f32_e32 v10, v10
	v_rcp_f32_e32 v11, v11
	v_pk_mul_f32 v[8:9], v[12:13], v[8:9]
	v_pk_mul_f32 v[12:13], v[16:17], v[32:33] op_sel_hi:[1,0]
	v_cvt_pk_bf16_f32 v8, v8, v9
	v_pk_mul_f32 v[10:11], v[10:11], v[14:15]
	s_nop 0
	v_permlane16_swap_b32_e32 v6, v8
	v_pk_mul_f32 v[10:11], v[12:13], v[10:11]
	s_nop 0
	v_cvt_pk_bf16_f32 v9, v10, v11
	v_mad_i64_i32 v[10:11], s[2:3], v33, s70, v[22:23]
	v_lshl_add_u64 v[10:11], v[10:11], 0, s[4:5]
	v_lshl_add_u64 v[10:11], v[10:11], 0, v[18:19]
	v_lshl_add_u64 v[10:11], v[10:11], 0, v[20:21]
	v_permlane16_swap_b32_e32 v7, v9
	global_store_dwordx4 v[10:11], v[2:5], off
	global_store_dwordx4 v[10:11], v[6:9], off offset:64
